# speedup vs baseline: 1.0046x; 1.0035x over previous
; __device__ __forceinline__ unsigned cvt_pk_bf16(float lo, float hi) { const f32x2 v = {lo, hi}; const bf16v2 r = __builtin_convertvector(v, bf16v2); return __builtin_bit_cast(unsigned, r); }
; __device__ void norm_phase(const float* xp, const float* xs, float* out, const float* gain, bf16_t* H, float* SSo) {
;     ...
;     for (int row = gw; row < T; row += nw) {
;         const float* xr = row < 8192 ? xp + (size_t)row * DM : xs + (size_t)(row - 8192) * DM;
;         f32x4 v[8]; float ss = 0.f;
; #pragma unroll
;         for (int j = 0; j < 8; ++j) { v[j] = *(const f32x4*)(xr + (lane + 64 * j) * 4); ss += v[j][0] * v[j][0] + v[j][1] * v[j][1] + v[j][2] * v[j][2] + v[j][3] * v[j][3]; }
; #pragma unroll
;         for (int o = 32; o >= 1; o >>= 1) ss += __shfl_xor(ss, o);
;         if (lane < 8) SSo[(size_t)lane * T + row] = lane == 0 ? ss : 0.f;
; #pragma unroll
;         for (int j = 0; j < 8; ++j) { const f32x4 g = *(const f32x4*)(gain + (lane + 64 * j) * 4);
;             u32x2 w; w.x = cvt_pk_bf16(v[j][0] * g[0], v[j][1] * g[1]); w.y = cvt_pk_bf16(v[j][2] * g[2], v[j][3] * g[3]);
;             *(u32x2*)(H + (size_t)row * DM + (lane + 64 * j) * 4) = w;
;             *(f32x4*)(out + (size_t)row * DM + (lane + 64 * j) * 4) = v[j]; }
.LBB0_390:
	v_readlane_b32 s40, v254, 45
	s_movk_i32 s6, 0x2000
	v_readlane_b32 s41, v254, 46
	v_readlane_b32 s43, v254, 48
	v_cmp_gt_i32_e64 s[38:39], s6, v44
	v_add_u32_e32 v2, 0xffffe000, v44
	v_readlane_b32 s42, v254, 47
	v_mov_b32_e32 v4, s43
	v_mov_b32_e32 v5, s41
	v_cndmask_b32_e64 v3, 0, v45, s[38:39]
	v_cndmask_b32_e64 v2, v2, v44, s[38:39]
	v_cndmask_b32_e64 v5, v4, v5, s[38:39]
	v_mov_b32_e32 v4, s42
	v_mov_b32_e32 v6, s40
	v_cndmask_b32_e64 v4, v4, v6, s[38:39]
	v_lshlrev_b64 v[2:3], 13, v[2:3]
	v_lshl_add_u64 v[30:31], v[4:5], 0, v[2:3]
	v_mov_b32_e32 v53, v1
	v_mov_b32_e32 v55, v1
	v_mov_b32_e32 v57, v1
	v_mov_b32_e32 v59, v1
	v_lshl_add_u64 v[70:71], v[30:31], 0, v[0:1]
	v_lshl_add_u64 v[72:73], v[30:31], 0, v[52:53]
	v_lshl_add_u64 v[74:75], v[30:31], 0, v[54:55]
	v_lshl_add_u64 v[76:77], v[30:31], 0, v[56:57]
	v_lshl_add_u64 v[78:79], v[30:31], 0, v[58:59]
	global_load_dwordx4 v[2:5], v[70:71], off nt
	global_load_dwordx4 v[6:9], v[70:71], off offset:1024 nt
	global_load_dwordx4 v[10:13], v[70:71], off offset:2048 nt
	global_load_dwordx4 v[14:17], v[70:71], off offset:3072 nt
	global_load_dwordx4 v[18:21], v[72:73], off nt
	global_load_dwordx4 v[22:25], v[74:75], off nt
	global_load_dwordx4 v[26:29], v[76:77], off nt
	global_load_dwordx4 v[30:33], v[78:79], off nt
	global_load_dwordx4 v[100:103], v[34:35], off
	global_load_dwordx4 v[104:107], v[34:35], off offset:1024
	global_load_dwordx4 v[108:111], v[34:35], off offset:2048
	global_load_dwordx4 v[112:115], v[34:35], off offset:3072
	global_load_dwordx4 v[116:119], v[36:37], off
	global_load_dwordx4 v[120:123], v[38:39], off
	global_load_dwordx4 v[124:127], v[40:41], off
	global_load_dwordx4 v[128:131], v[42:43], off
	s_waitcnt lgkmcnt(0)
	v_readlane_b32 s44, v254, 49
	v_readlane_b32 s45, v254, 50
	v_readlane_b32 s46, v254, 51
	v_readlane_b32 s47, v254, 52
	v_readlane_b32 s48, v254, 53
	v_readlane_b32 s49, v254, 54
	v_readlane_b32 s50, v254, 55
	v_readlane_b32 s51, v254, 56
	v_readlane_b32 s52, v254, 57
	v_readlane_b32 s53, v254, 58
	v_readlane_b32 s54, v254, 59
	v_readlane_b32 s55, v254, 60
	s_waitcnt vmcnt(8)
	v_mul_f32_e32 v80, v3, v3
	v_fmac_f32_e32 v80, v2, v2
	v_fmac_f32_e32 v80, v4, v4
	v_fmac_f32_e32 v80, v5, v5
	v_mul_f32_e32 v81, v7, v7
	v_fmac_f32_e32 v81, v6, v6
	v_fmac_f32_e32 v81, v8, v8
	v_fmac_f32_e32 v81, v9, v9
	v_add_f32_e32 v80, v80, v81
	v_mul_f32_e32 v81, v11, v11
	v_fmac_f32_e32 v81, v10, v10
	v_fmac_f32_e32 v81, v12, v12
	v_fmac_f32_e32 v81, v13, v13
	v_add_f32_e32 v80, v80, v81
	v_mul_f32_e32 v81, v15, v15
	v_fmac_f32_e32 v81, v14, v14
	v_fmac_f32_e32 v81, v16, v16
	v_fmac_f32_e32 v81, v17, v17
	v_add_f32_e32 v80, v80, v81
	v_mul_f32_e32 v81, v19, v19
	v_fmac_f32_e32 v81, v18, v18
	v_fmac_f32_e32 v81, v20, v20
	v_fmac_f32_e32 v81, v21, v21
	v_add_f32_e32 v80, v80, v81
	v_mul_f32_e32 v81, v23, v23
	v_fmac_f32_e32 v81, v22, v22
	v_fmac_f32_e32 v81, v24, v24
	v_fmac_f32_e32 v81, v25, v25
	v_add_f32_e32 v80, v80, v81
	v_mul_f32_e32 v81, v27, v27
	v_fmac_f32_e32 v81, v26, v26
	v_fmac_f32_e32 v81, v28, v28
	v_fmac_f32_e32 v81, v29, v29
	v_add_f32_e32 v80, v80, v81
	v_mul_f32_e32 v81, v31, v31
	v_fmac_f32_e32 v81, v30, v30
	v_fmac_f32_e32 v81, v32, v32
	v_fmac_f32_e32 v81, v33, v33
	v_add_f32_e32 v80, v80, v81
	v_mov_b32_e32 v53, v80
	ds_bpermute_b32 v55, v60, v53
	s_waitcnt lgkmcnt(0)
	v_add_f32_e32 v53, v53, v55
	ds_bpermute_b32 v55, v61, v53
	s_waitcnt lgkmcnt(0)
	v_add_f32_e32 v53, v53, v55
	ds_bpermute_b32 v55, v62, v53
	s_waitcnt lgkmcnt(0)
	v_add_f32_e32 v53, v53, v55
	ds_bpermute_b32 v55, v63, v53
	s_waitcnt lgkmcnt(0)
	v_add_f32_e32 v53, v53, v55
	ds_bpermute_b32 v55, v64, v53
	s_waitcnt lgkmcnt(0)
	v_add_f32_e32 v53, v53, v55
	ds_bpermute_b32 v55, v65, v53
	s_and_saveexec_b64 s[6:7], vcc
	s_cbranch_execz .LBB0_389
	s_waitcnt lgkmcnt(0)
	v_add_f32_e32 v53, v53, v55
	v_cndmask_b32_e64 v53, 0, v53, s[0:1]
	global_store_dword v[46:47], v53, off
	s_branch .LBB0_389
